# finalize-phase items scheduled per out-proj row-block group; st3->st4 seam joins the 4-workgroup barrier chain; probability buffer P moved off the U overlay (K-tail/V image area, dead after attention)
# speedup vs baseline: 1.0212x; 1.0080x over previous
.LBB0_710:
	s_andn2_b64 vcc, exec, s[2:3]
	s_cbranch_vccnz .LBB0_736
	v_readlane_b32 s0, v255, 45
	v_mov_b32_e32 v180, v184
	s_cmpk_gt_i32 s0, 0xff
	s_cbranch_scc1 .LBB0_736
	v_ashrrev_i32_e32 v2, 6, v180
	v_and_b32_e32 v3, 31, v180
	v_ashrrev_i32_e32 v4, 8, v180
	v_and_b32_e32 v181, 3, v2
	v_lshlrev_b32_e32 v0, 7, v3
	v_lshl_or_b32 v182, v4, 14, v0
	v_lshl_or_b32 v204, v181, 13, v0
	v_bfe_u32 v0, v180, 3, 3
	v_lshl_or_b32 v207, v2, 3, v0
	v_lshrrev_b32_e32 v0, 1, v207
	v_xor_b32_e32 v0, v0, v180
	v_lshlrev_b32_e32 v0, 4, v0
	s_add_u32 s18, s82, 0x6a51000
	v_and_b32_e32 v168, 0x70, v0
	s_addc_u32 s19, s83, 0
	v_lshl_add_u64 v[0:1], s[82:83], 0, v[168:169]
	s_mov_b64 s[0:1], 0x6570000
	v_lshl_add_u64 v[144:145], v[0:1], 0, s[0:1]
	s_mov_b64 s[0:1], 0xc3b9000
	s_cmp_lg_u32 16, -1
	v_lshl_add_u64 v[146:147], v[0:1], 0, s[0:1]
	v_lshlrev_b32_e32 v209, 10, v2
	s_cselect_b32 s0, 16, 0
	v_add_u32_e32 v210, s0, v209
	v_lshlrev_b32_e32 v211, 5, v2
	v_lshlrev_b32_e32 v1, 15, v4
	v_lshlrev_b32_e32 v2, 8, v3
	s_add_i32 s0, 16, 0x12000
	v_add3_u32 v223, s0, v1, v2
	s_add_i32 s0, 16, 0x14000
	v_bfe_u32 v5, v180, 5, 1
	v_bfe_u32 v212, v180, 4, 2
	s_add_i32 s20, 16, 0x10000
	v_add3_u32 v224, s0, v1, v2
	s_add_i32 s0, 16, 0x16000
	v_and_b32_e32 v0, 15, v180
	v_add3_u32 v214, s20, v1, v2
	v_bitop3_b32 v3, v5, v180, 15 bitop3:0x78
	v_add3_u32 v225, s0, v1, v2
	v_xor_b32_e32 v1, v212, v180
	v_lshlrev_b32_e32 v215, 4, v3
	v_bitop3_b32 v3, v5, v0, 2 bitop3:0x36
	v_lshlrev_b32_e32 v1, 4, v1
	v_lshrrev_b32_e32 v6, 1, v180
	v_lshlrev_b32_e32 v216, 4, v3
	v_bitop3_b32 v3, v5, v0, 4 bitop3:0x36
	v_and_b32_e32 v1, 0xf0, v1
	v_bfe_u32 v7, v180, 1, 3
	v_lshlrev_b32_e32 v217, 4, v3
	v_bitop3_b32 v3, v5, v0, 6 bitop3:0x36
	v_add_u32_e32 v226, s20, v1
	v_bitop3_b32 v1, v6, v5, 7 bitop3:0x6c
	v_lshlrev_b32_e32 v218, 4, v3
	v_bitop3_b32 v3, v5, v0, 8 bitop3:0x36
	v_lshlrev_b32_e32 v227, 4, v1
	v_bitop3_b32 v1, v5, v7, 2 bitop3:0x36
	v_lshlrev_b32_e32 v219, 4, v3
	v_bitop3_b32 v3, v5, v0, 10 bitop3:0x36
	v_lshlrev_b32_e32 v228, 4, v1
	v_bitop3_b32 v1, v5, v7, 4 bitop3:0x36
	v_lshlrev_b32_e32 v220, 4, v3
	v_bitop3_b32 v3, v5, v0, 12 bitop3:0x36
	v_lshlrev_b32_e32 v229, 4, v1
	v_bitop3_b32 v1, v5, v7, 6 bitop3:0x36
	v_lshlrev_b32_e32 v221, 4, v3
	v_bitop3_b32 v3, v5, v0, 14 bitop3:0x36
	v_lshlrev_b32_e32 v230, 4, v1
	v_lshlrev_b32_e32 v168, 4, v0
	v_or_b32_e32 v183, 0x1000, v182
	v_or_b32_e32 v202, 0x2000, v182
	v_or_b32_e32 v203, 0x3000, v182
	v_or_b32_e32 v205, 0x8000, v204
	v_or_b32_e32 v206, 0x9000, v204
	v_add_u32_e32 v208, 0xffffff00, v207
	v_lshlrev_b32_e32 v213, 2, v0
	v_cmp_eq_u32_e64 s[6:7], 0, v0
	v_lshlrev_b32_e32 v222, 4, v3
	v_add_u32_e32 v231, s20, v182
	v_lshl_add_u64 v[148:149], s[4:5], 0, v[168:169]
	v_add_u32_e32 v232, s20, v227
	v_add_u32_e32 v233, s20, v228
	v_add_u32_e32 v234, s20, v229
	v_add_u32_e32 v235, s20, v230
	s_mov_b64 s[8:9], 0
	v_readlane_b32 s21, v255, 45
	s_mov_b64 s[34:35], 0x80000
	s_mov_b64 s[36:37], 0xc0000
	s_mov_b64 s[38:39], 0xa0000
	s_mov_b64 s[40:41], 0xe0000
	s_branch .LBB0_714

.LBB0_737:
	s_andn2_b64 vcc, exec, s[2:3]
	s_cbranch_vccnz .LBB0_797
	v_readlane_b32 s0, v255, 46
	s_cmp_gt_i32 s0, 4
	s_mov_b64 s[2:3], -1
	s_cbranch_scc0 .LBB0_769
	v_readlane_b32 s0, v255, 45
	v_mov_b32_e32 v150, v184
	s_cmpk_gt_i32 s0, 0xff
	s_mov_b32 s22, 0xff61b1e6
	s_mov_b64 s[30:31], 0x80000
	s_mov_b64 s[34:35], 0xc0000
	s_mov_b64 s[36:37], 0xa0000
	s_mov_b64 s[38:39], 0xe0000
	s_cbranch_scc1 .LBB0_768
	v_ashrrev_i32_e32 v0, 6, v150
	v_ashrrev_i32_e32 v2, 8, v150
	v_bfe_u32 v8, v150, 3, 3
	s_add_u32 s10, s82, 0xc3b9000
	v_and_b32_e32 v1, 31, v150
	v_and_b32_e32 v3, 3, v0
	v_bfe_u32 v5, v150, 5, 1
	v_lshrrev_b32_e32 v6, 1, v150
	v_lshl_or_b32 v158, v0, 3, v8
	v_lshlrev_b32_e32 v160, 10, v0
	v_lshlrev_b32_e32 v0, 7, v2
	s_addc_u32 s11, s83, 0
	v_lshlrev_b32_e32 v4, 7, v1
	v_bfe_u32 v7, v150, 1, 3
	v_lshlrev_b32_e32 v9, 2, v1
	v_and_or_b32 v10, v0, s69, v1
	v_or_b32_e32 v167, v0, v1
	v_bitop3_b32 v1, v6, v5, 7 bitop3:0x6c
	s_add_u32 s12, s82, 0x6a51000
	v_lshlrev_b32_e32 v171, 4, v1
	v_bitop3_b32 v1, v5, v7, 2 bitop3:0x36
	s_addc_u32 s13, s83, 0
	s_add_i32 s0, 16, 0x20000
	v_lshrrev_b32_e32 v8, 1, v158
	v_lshlrev_b32_e32 v172, 4, v1
	v_bitop3_b32 v1, v5, v7, 4 bitop3:0x36
	v_lshl_or_b32 v151, v2, 14, v4
	v_xor_b32_e32 v8, v8, v150
	s_cmp_lg_u32 16, -1
	v_lshlrev_b32_e32 v2, 9, v2
	v_lshlrev_b32_e32 v173, 4, v1
	v_bitop3_b32 v1, v5, v7, 6 bitop3:0x36
	s_cselect_b32 s1, 16, 0
	v_lshl_add_u32 v162, v150, 2, s0
	v_add3_u32 v164, s0, v9, v2
	v_lshlrev_b32_e32 v2, 4, v10
	s_add_i32 s0, 16, 0x20400
	v_lshlrev_b32_e32 v174, 4, v1
	v_lshlrev_b32_e32 v1, 4, v8
	v_add_u32_e32 v165, s0, v2
	s_add_i32 s0, 16, 0x21400
	v_and_b32_e32 v168, 0x70, v1
	v_lshl_or_b32 v155, v3, 13, v4
	v_and_b32_e32 v4, 63, v150
	v_add_u32_e32 v161, s1, v160
	v_lshlrev_b32_e32 v163, 6, v3
	v_lshl_add_u32 v166, v3, 2, v165
	v_lshlrev_b32_e32 v0, 3, v5
	v_add_u32_e32 v170, s0, v2
	s_add_i32 s2, 16, 0x10000
	v_lshl_add_u64 v[2:3], s[82:83], 0, v[168:169]
	s_mov_b64 s[0:1], 0x6170000
	v_or_b32_e32 v152, 0x1000, v151
	v_or_b32_e32 v153, 0x2000, v151
	v_or_b32_e32 v154, 0x3000, v151
	v_or_b32_e32 v156, 0x8000, v155
	v_or_b32_e32 v157, 0x9000, v155
	v_add_u32_e32 v159, 0xffffff00, v158
	v_cmp_gt_i32_e64 s[6:7], s70, v150
	v_cmp_gt_u32_e64 s[8:9], 32, v4
	v_add_u32_e32 v175, s2, v151
	v_lshl_add_u64 v[128:129], v[2:3], 0, s[0:1]
	v_lshl_add_u64 v[130:131], s[24:25], 0, v[168:169]
	v_add_u32_e32 v176, s2, v171
	v_add_u32_e32 v177, s2, v172
	v_add_u32_e32 v178, s2, v173
	v_add_u32_e32 v179, s2, v174
	s_mov_b64 s[14:15], 0
	v_lshlrev_b32_e32 v132, 1, v0
	v_readlane_b32 s18, v255, 45
	s_branch .LBB0_742

.LBB0_798:
	s_andn2_b64 vcc, exec, s[2:3]
	s_cbranch_vccnz .LBB0_1364
	v_readlane_b32 s0, v255, 46
	s_cmp_lt_i32 s0, 2
	s_mov_b64 s[2:3], -1
	s_cbranch_scc1 .LBB0_873
	v_readlane_b32 s0, v255, 46
	s_cmp_gt_i32 s0, 2
	s_cbranch_scc0 .LBB0_809
	s_cmpk_gt_i32 s45, 0x4ff
	s_mov_b32 s29, 0x6bb9000
	s_cbranch_scc1 .LBB0_808
	s_add_u32 s4, s82, 0xa3b9000
	s_addc_u32 s5, s83, 0
	s_add_u32 s6, s82, 0xe3b9000
	s_addc_u32 s7, s83, 0
	s_add_u32 s8, s82, 0x10bb9000
	s_addc_u32 s9, s83, 0
	s_add_u32 s10, s82, 0x113b9000
	s_addc_u32 s11, s83, 0
	s_add_u32 s12, s82, 0x6a31000
	s_addc_u32 s13, s83, 0
	s_add_u32 s14, s82, 0x103b9000
	s_addc_u32 s15, s83, 0
	s_add_u32 s16, s82, 0x69b0000
	s_addc_u32 s17, s83, 0
	s_and_b32 s0, s45, 1
	s_lshl_b32 s1, s0, 7
	s_add_u32 s2, s82, s1
	s_addc_u32 s3, s83, 0
	s_add_u32 s18, s2, 0x107b9000
	s_addc_u32 s19, s3, 0
	s_lshl_b32 s22, s0, 1
	s_lshl_b32 s0, s0, 8
	s_add_u32 s0, s82, s0
	s_addc_u32 s2, s83, 0
	s_add_u32 s20, s0, 0xf3b9000
	s_addc_u32 s21, s2, 0
	s_lshl_b32 s0, s45, 4
	s_or_b32 s23, s22, 1
	s_add_i32 s27, s0, 0xfffff000
	s_lshl_b32 s30, s78, 5
	s_lshl_b32 s52, s1, 1
	s_mov_b32 s31, s45
	s_cmpk_lg_u32 s80, 0x200
	s_cbranch_scc1 .Lst3_i_done
	s_lshr_b32 s33, s45, 1
	s_and_b32 s34, s33, 7
	s_lshl_b32 s34, s34, 3
	s_lshr_b32 s35, s33, 5
	s_add_i32 s34, s34, s35
	s_bfe_u32 s35, s33, 0x20003
	s_lshl_b32 s35, s35, 1
	s_and_b32 s33, s45, 1
	s_add_i32 s35, s35, s33
	s_lshl_b32 s32, s34, 4
	s_lshl_b32 s33, s35, 1
	s_add_i32 s32, s32, s33
	s_addk_i32 s32, 0x100
	s_lshl_b32 s34, s34, 2
	s_add_i32 s31, s34, s35
	s_cmp_lt_u32 s35, 4
	s_cselect_b32 s31, s31, s32
	s_lshl_b32 s27, s31, 4
	s_add_i32 s27, s27, 0xfffff000

.LBB0_803:
	s_cmpk_lg_u32 s80, 0x200
	s_cbranch_scc1 .Lst3_gen
	s_cmpk_lt_u32 s31, 0x100
	s_cbranch_scc1 .Lst3_first
	s_bitcmp1_b32 s31, 0
	s_cbranch_scc1 .LBB0_808
	s_add_i32 s31, s31, 1
	s_branch .Lst3_set
.Lst3_first:
	s_mov_b32 s31, s32
.Lst3_set:
	s_lshl_b32 s27, s31, 4
	s_add_i32 s27, s27, 0xfffff000
	s_branch .LBB0_804

.LBB0_2018:
	s_add_i32 s0, s29, -1
	s_cmp_lt_i32 s0, 0
	s_cbranch_scc1 .Lgb_no
	s_mul_i32 s1, s0, 57
	s_lshr_b32 s1, s1, 9
	s_mul_i32 s2, s1, 9
	s_sub_i32 s2, s0, s2
	s_add_i32 s2, s2, -3
	s_cmp_gt_u32 s2, 2
	s_cbranch_scc1 .Lgb_no
	s_mul_i32 s1, s1, 3
	s_add_i32 s1, s1, s2
	s_add_i32 s1, s1, 1
	s_lshl_b32 s1, s1, 2
	v_readlane_b32 s3, v255, 60
	s_cmp_lg_u32 s3, 0
	s_cbranch_scc1 .Lgb_known
	v_lshlrev_b32_e32 v0, 3, v191
	v_add_u32_e32 v0, 0xa000, v0
	global_load_dwordx2 v[0:1], v0, s[82:83] sc1
	s_waitcnt vmcnt(0)
	v_add_u32_e32 v0, v0, v1
	v_cmp_ne_u32_e32 vcc, 15, v0
	s_cmp_lg_u64 vcc, 0
	s_cselect_b32 s3, 2, 1
	s_nop 0
	v_writelane_b32 v255, s3, 60
